# mLSTM output unit: the two 8-deep LDS read->wait->MFMA chains issue their reads up front into dead fragment registers and wait progressively
# baseline (speedup 1.0000x reference)
.LBB0_681:
	s_cmp_gt_u32 s61, 1
	s_cselect_b64 s[6:7], -1, 0
	s_cmp_eq_u32 s61, 3
	s_cselect_b64 s[0:1], -1, 0
	s_xor_b64 s[10:11], s[14:15], -1
	s_or_b64 s[0:1], s[0:1], s[10:11]
	s_or_b64 s[10:11], s[0:1], s[6:7]
	s_andn2_b64 vcc, exec, s[10:11]
	s_cbranch_vccnz .LBB0_688
	s_cmp_lg_u32 s61, 3
	s_cselect_b64 s[10:11], -1, 0
	v_cndmask_b32_e64 v66, 0, 1, s[10:11]
	v_cndmask_b32_e64 v67, 0, 1, s[6:7]
	v_cndmask_b32_e64 v66, v66, v67, s[14:15]
	v_and_b32_e32 v66, 1, v66
	v_cmp_eq_u32_e32 vcc, 0, v66
	v_mov_b32_e32 v115, 0
	v_mov_b32_e32 v119, 0
	s_and_b64 vcc, exec, vcc
	v_add_u32_e32 v160, v156, v147
	v_add_u32_e32 v159, v156, v148
	v_add_u32_e32 v158, v156, v149
	v_add_u32_e32 v149, v156, v150
	v_add_u32_e32 v148, v156, v151
	v_add_u32_e32 v147, v156, v152
	v_add_u32_e32 v133, v156, v153
	v_add_u32_e32 v132, v156, v155
	v_lshl_add_u32 v114, v146, 2, s94
	s_cbranch_vccnz .LBB0_685
	ds_read_b128 v[66:69], v160 offset:49152
	ds_read_b128 v[116:119], v159 offset:49152
	ds_read_b128 v[228:231], v158 offset:49152
	ds_read_b128 v[232:235], v149 offset:49152
	ds_read_b128 v[236:239], v148 offset:49152
	ds_read_b128 v[240:243], v147 offset:49152
	ds_read_b128 v[244:247], v133 offset:49152
	ds_read_b128 v[248:251], v132 offset:49152
	s_waitcnt lgkmcnt(7)
	v_mfma_f32_32x32x16_bf16 v[66:81], v[66:69], v[110:113], 0
	s_waitcnt lgkmcnt(6)
	v_mfma_f32_32x32x16_bf16 v[66:81], v[116:119], v[106:109], v[66:81]
	s_waitcnt lgkmcnt(5)
	v_mfma_f32_32x32x16_bf16 v[66:81], v[228:231], v[102:105], v[66:81]
	s_waitcnt lgkmcnt(4)
	v_mfma_f32_32x32x16_bf16 v[66:81], v[232:235], v[94:97], v[66:81]
	s_waitcnt lgkmcnt(3)
	v_mfma_f32_32x32x16_bf16 v[66:81], v[236:239], v[98:101], v[66:81]
	s_waitcnt lgkmcnt(2)
	v_mfma_f32_32x32x16_bf16 v[66:81], v[240:243], v[86:89], v[66:81]
	s_waitcnt lgkmcnt(1)
	v_mfma_f32_32x32x16_bf16 v[66:81], v[244:247], v[90:93], v[66:81]
	s_waitcnt lgkmcnt(0)
	v_mfma_f32_32x32x16_bf16 v[66:81], v[248:251], v[82:85], v[66:81]
	v_or_b32_e32 v116, 64, v146
	v_sub_u32_e32 v116, v141, v116
	v_mul_i32_i24_e32 v116, s8, v116
	v_ashrrev_i32_e32 v116, 31, v116
	v_cvt_f32_i32_e32 v124, v116
	ds_read_b128 v[120:123], v114 offset:768
	ds_read_b128 v[116:119], v114 offset:800
	s_waitcnt lgkmcnt(1)
	v_add_f32_e32 v120, v145, v120
	v_fmac_f32_e32 v120, 0x7149f2ca, v124
	v_or_b32_e32 v124, 0x41, v146
	v_sub_u32_e32 v124, v141, v124
	v_mul_i32_i24_e32 v124, s8, v124
	v_ashrrev_i32_e32 v124, 31, v124
	v_cvt_f32_i32_e32 v124, v124
	v_add_f32_e32 v121, v145, v121
	v_mul_f32_e32 v120, 0x3fb8aa3b, v120
	v_exp_f32_e32 v120, v120
	v_fmac_f32_e32 v121, 0x7149f2ca, v124
	v_mul_f32_e32 v121, 0x3fb8aa3b, v121
	v_exp_f32_e32 v121, v121
	s_nop 0
	v_pk_mul_f32 v[120:121], v[66:67], v[120:121]
	s_nop 0
	v_add_f32_e32 v66, v157, v120
	v_add_f32_e32 v124, v66, v121
	v_or_b32_e32 v66, 0x42, v146
	v_sub_u32_e32 v66, v141, v66
	v_mul_i32_i24_e32 v66, s8, v66
	v_ashrrev_i32_e32 v66, 31, v66
	v_cvt_f32_i32_e32 v66, v66
	v_add_f32_e32 v67, v145, v122
	v_add_f32_e32 v122, v145, v123
	v_fmac_f32_e32 v67, 0x7149f2ca, v66
	v_mul_f32_e32 v66, 0x3fb8aa3b, v67
	v_or_b32_e32 v67, 0x43, v146
	v_sub_u32_e32 v67, v141, v67
	v_mul_i32_i24_e32 v67, s8, v67
	v_ashrrev_i32_e32 v67, 31, v67
	v_cvt_f32_i32_e32 v67, v67
	v_exp_f32_e32 v66, v66
	v_fmac_f32_e32 v122, 0x7149f2ca, v67
	v_mul_f32_e32 v67, 0x3fb8aa3b, v122
	v_exp_f32_e32 v67, v67
	s_nop 0
	v_pk_mul_f32 v[122:123], v[68:69], v[66:67]
	s_nop 0
	v_add_f32_e32 v66, v124, v122
	v_add_f32_e32 v68, v66, v123
	v_or_b32_e32 v66, 0x48, v146
	v_sub_u32_e32 v66, v141, v66
	v_mul_i32_i24_e32 v66, s8, v66
	v_ashrrev_i32_e32 v66, 31, v66
	v_cvt_f32_i32_e32 v66, v66
	s_waitcnt lgkmcnt(0)
	v_add_f32_e32 v67, v145, v116
	v_add_f32_e32 v69, v145, v117
	v_fmac_f32_e32 v67, 0x7149f2ca, v66
	v_mul_f32_e32 v66, 0x3fb8aa3b, v67
	v_or_b32_e32 v67, 0x49, v146
	v_sub_u32_e32 v67, v141, v67
	v_mul_i32_i24_e32 v67, s8, v67
	v_ashrrev_i32_e32 v67, 31, v67
	v_cvt_f32_i32_e32 v67, v67
	v_exp_f32_e32 v66, v66
	v_fmac_f32_e32 v69, 0x7149f2ca, v67
	v_mul_f32_e32 v67, 0x3fb8aa3b, v69
	v_exp_f32_e32 v67, v67
	v_add_f32_e32 v69, v145, v119
	v_pk_mul_f32 v[116:117], v[70:71], v[66:67]
	s_nop 0
	v_add_f32_e32 v66, v68, v116
	v_add_f32_e32 v68, v66, v117
	v_or_b32_e32 v66, 0x4a, v146
	v_sub_u32_e32 v66, v141, v66
	v_mul_i32_i24_e32 v66, s8, v66
	v_ashrrev_i32_e32 v66, 31, v66
	v_cvt_f32_i32_e32 v66, v66
	v_add_f32_e32 v67, v145, v118
	v_fmac_f32_e32 v67, 0x7149f2ca, v66
	v_mul_f32_e32 v66, 0x3fb8aa3b, v67
	v_or_b32_e32 v67, 0x4b, v146
	v_sub_u32_e32 v67, v141, v67
	v_mul_i32_i24_e32 v67, s8, v67
	v_ashrrev_i32_e32 v67, 31, v67
	v_cvt_f32_i32_e32 v67, v67
	v_exp_f32_e32 v66, v66
	v_fmac_f32_e32 v69, 0x7149f2ca, v67
	v_mul_f32_e32 v67, 0x3fb8aa3b, v69
	v_exp_f32_e32 v67, v67
	s_nop 0
	v_pk_mul_f32 v[124:125], v[72:73], v[66:67]
	s_nop 0
	v_add_f32_e32 v66, v68, v124
	v_add_f32_e32 v70, v66, v125
	v_or_b32_e32 v66, 0x50, v146
	v_sub_u32_e32 v66, v141, v66
	v_mul_i32_i24_e32 v66, s8, v66
	v_ashrrev_i32_e32 v66, 31, v66
	v_cvt_f32_i32_e32 v71, v66
	ds_read_b128 v[66:69], v114 offset:832
	s_waitcnt lgkmcnt(0)
	v_add_f32_e32 v66, v145, v66
	v_fmac_f32_e32 v66, 0x7149f2ca, v71
	v_or_b32_e32 v71, 0x51, v146
	v_sub_u32_e32 v71, v141, v71
	v_mul_i32_i24_e32 v71, s8, v71
	v_ashrrev_i32_e32 v71, 31, v71
	v_cvt_f32_i32_e32 v71, v71
	v_add_f32_e32 v67, v145, v67
	v_mul_f32_e32 v66, 0x3fb8aa3b, v66
	v_exp_f32_e32 v66, v66
	v_fmac_f32_e32 v67, 0x7149f2ca, v71
	v_mul_f32_e32 v67, 0x3fb8aa3b, v67
	v_exp_f32_e32 v67, v67
	s_nop 0
	v_pk_mul_f32 v[126:127], v[74:75], v[66:67]
	s_nop 0
	v_add_f32_e32 v66, v70, v126
	v_add_f32_e32 v70, v66, v127
	v_or_b32_e32 v66, 0x52, v146
	v_sub_u32_e32 v66, v141, v66
	v_mul_i32_i24_e32 v66, s8, v66
	v_ashrrev_i32_e32 v66, 31, v66
	v_cvt_f32_i32_e32 v66, v66
	v_add_f32_e32 v67, v145, v68
	v_add_f32_e32 v68, v145, v69
	v_fmac_f32_e32 v67, 0x7149f2ca, v66
	v_mul_f32_e32 v66, 0x3fb8aa3b, v67
	v_or_b32_e32 v67, 0x53, v146
	v_sub_u32_e32 v67, v141, v67
	v_mul_i32_i24_e32 v67, s8, v67
	v_ashrrev_i32_e32 v67, 31, v67
	v_cvt_f32_i32_e32 v67, v67
	v_exp_f32_e32 v66, v66
	v_fmac_f32_e32 v68, 0x7149f2ca, v67
	v_mul_f32_e32 v67, 0x3fb8aa3b, v68
	v_exp_f32_e32 v67, v67
	s_nop 0
	v_pk_mul_f32 v[128:129], v[76:77], v[66:67]
	s_nop 0
	v_add_f32_e32 v66, v70, v128
	v_add_f32_e32 v70, v66, v129
	v_or_b32_e32 v66, 0x58, v146
	v_sub_u32_e32 v66, v141, v66
	v_mul_i32_i24_e32 v66, s8, v66
	v_ashrrev_i32_e32 v66, 31, v66
	v_cvt_f32_i32_e32 v71, v66
	ds_read_b128 v[66:69], v114 offset:864
	s_waitcnt lgkmcnt(0)
	v_add_f32_e32 v66, v145, v66
	v_fmac_f32_e32 v66, 0x7149f2ca, v71
	v_or_b32_e32 v71, 0x59, v146
	v_sub_u32_e32 v71, v141, v71
	v_mul_i32_i24_e32 v71, s8, v71
	v_ashrrev_i32_e32 v71, 31, v71
	v_cvt_f32_i32_e32 v71, v71
	v_add_f32_e32 v67, v145, v67
	v_mul_f32_e32 v66, 0x3fb8aa3b, v66
	v_exp_f32_e32 v66, v66
	v_fmac_f32_e32 v67, 0x7149f2ca, v71
	v_mul_f32_e32 v67, 0x3fb8aa3b, v67
	v_exp_f32_e32 v67, v67
	s_nop 0
	v_pk_mul_f32 v[130:131], v[78:79], v[66:67]
	s_nop 0
	v_add_f32_e32 v66, v70, v130
	v_add_f32_e32 v70, v66, v131
	v_or_b32_e32 v66, 0x5a, v146
	v_sub_u32_e32 v66, v141, v66
	v_mul_i32_i24_e32 v66, s8, v66
	v_ashrrev_i32_e32 v66, 31, v66
	v_cvt_f32_i32_e32 v66, v66
	v_add_f32_e32 v67, v145, v68
	v_add_f32_e32 v68, v145, v69
	v_fmac_f32_e32 v67, 0x7149f2ca, v66
	v_mul_f32_e32 v66, 0x3fb8aa3b, v67
	v_or_b32_e32 v67, 0x5b, v146
	v_sub_u32_e32 v67, v141, v67
	v_mul_i32_i24_e32 v67, s8, v67
	v_ashrrev_i32_e32 v67, 31, v67
	v_cvt_f32_i32_e32 v67, v67
	v_exp_f32_e32 v66, v66
	v_fmac_f32_e32 v68, 0x7149f2ca, v67
	v_mul_f32_e32 v67, 0x3fb8aa3b, v68
	v_exp_f32_e32 v67, v67
	s_nop 0
	v_pk_mul_f32 v[66:67], v[80:81], v[66:67]
	s_nop 0
	v_add_f32_e32 v68, v70, v66
	v_add_f32_e32 v157, v68, v67
	v_cvt_pk_bf16_f32 v119, v66, v67
	s_andn2_b64 vcc, exec, s[0:1]
	s_cbranch_vccz .LBB0_686

.LBB0_686:
	ds_read_b128 v[66:69], v160 offset:57344
	ds_read_b128 v[228:231], v159 offset:57344
	ds_read_b128 v[232:235], v158 offset:57344
	ds_read_b128 v[236:239], v149 offset:57344
	ds_read_b128 v[240:243], v148 offset:57344
	ds_read_b128 v[244:247], v147 offset:57344
	ds_read_b128 v[248:251], v133 offset:57344
	s_waitcnt lgkmcnt(6)
	v_mfma_f32_32x32x16_bf16 v[66:81], v[66:69], v[110:113], 0
	s_waitcnt lgkmcnt(5)
	v_mfma_f32_32x32x16_bf16 v[66:81], v[228:231], v[106:109], v[66:81]
	s_waitcnt lgkmcnt(4)
	v_mfma_f32_32x32x16_bf16 v[66:81], v[232:235], v[102:105], v[66:81]
	s_waitcnt lgkmcnt(3)
	v_mfma_f32_32x32x16_bf16 v[66:81], v[236:239], v[94:97], v[66:81]
	s_waitcnt lgkmcnt(2)
	v_mfma_f32_32x32x16_bf16 v[66:81], v[240:243], v[98:101], v[66:81]
	s_waitcnt lgkmcnt(1)
	v_mfma_f32_32x32x16_bf16 v[66:81], v[244:247], v[86:89], v[66:81]
	s_waitcnt lgkmcnt(0)
	v_mfma_f32_32x32x16_bf16 v[66:81], v[248:251], v[90:93], v[66:81]
	ds_read_b128 v[86:89], v132 offset:57344
	s_waitcnt lgkmcnt(0)
	v_mfma_f32_32x32x16_bf16 v[66:81], v[86:89], v[82:85], v[66:81]
	v_or_b32_e32 v82, 0x60, v146
	v_sub_u32_e32 v82, v141, v82
	v_mul_i32_i24_e32 v82, s8, v82
	v_ashrrev_i32_e32 v82, 31, v82
	v_cvt_f32_i32_e32 v90, v82
	ds_read_b128 v[86:89], v114 offset:896
	ds_read_b128 v[82:85], v114 offset:928
	s_waitcnt lgkmcnt(1)
	v_add_f32_e32 v86, v145, v86
	v_fmac_f32_e32 v86, 0x7149f2ca, v90
	v_or_b32_e32 v90, 0x61, v146
	v_sub_u32_e32 v90, v141, v90
	v_mul_i32_i24_e32 v90, s8, v90
	v_ashrrev_i32_e32 v90, 31, v90
	v_cvt_f32_i32_e32 v90, v90
	v_add_f32_e32 v87, v145, v87
	v_mul_f32_e32 v86, 0x3fb8aa3b, v86
	v_exp_f32_e32 v86, v86
	v_fmac_f32_e32 v87, 0x7149f2ca, v90
	v_mul_f32_e32 v87, 0x3fb8aa3b, v87
	v_exp_f32_e32 v87, v87
	s_waitcnt lgkmcnt(0)
	v_add_f32_e32 v82, v145, v82
	v_add_f32_e32 v83, v145, v83
	v_pk_mul_f32 v[66:67], v[66:67], v[86:87]
	s_nop 0
	v_add_f32_e32 v86, v157, v66
	v_add_f32_e32 v90, v86, v67
	v_or_b32_e32 v86, 0x62, v146
	v_sub_u32_e32 v86, v141, v86
	v_mul_i32_i24_e32 v86, s8, v86
	v_ashrrev_i32_e32 v86, 31, v86
	v_cvt_f32_i32_e32 v86, v86
	v_add_f32_e32 v87, v145, v88
	v_add_f32_e32 v88, v145, v89
	v_fmac_f32_e32 v87, 0x7149f2ca, v86
	v_mul_f32_e32 v86, 0x3fb8aa3b, v87
	v_or_b32_e32 v87, 0x63, v146
	v_sub_u32_e32 v87, v141, v87
	v_mul_i32_i24_e32 v87, s8, v87
	v_ashrrev_i32_e32 v87, 31, v87
	v_cvt_f32_i32_e32 v87, v87
	v_exp_f32_e32 v86, v86
	v_fmac_f32_e32 v88, 0x7149f2ca, v87
	v_mul_f32_e32 v87, 0x3fb8aa3b, v88
	v_exp_f32_e32 v87, v87
	s_nop 0
	v_pk_mul_f32 v[68:69], v[68:69], v[86:87]
	v_or_b32_e32 v87, 0x68, v146
	v_sub_u32_e32 v87, v141, v87
	v_mul_i32_i24_e32 v87, s8, v87
	v_ashrrev_i32_e32 v87, 31, v87
	v_cvt_f32_i32_e32 v87, v87
	v_add_f32_e32 v86, v90, v68
	v_add_f32_e32 v86, v86, v69
	v_fmac_f32_e32 v82, 0x7149f2ca, v87
	v_or_b32_e32 v87, 0x69, v146
	v_sub_u32_e32 v87, v141, v87
	v_mul_i32_i24_e32 v87, s8, v87
	v_ashrrev_i32_e32 v87, 31, v87
	v_cvt_f32_i32_e32 v87, v87
	v_mul_f32_e32 v82, 0x3fb8aa3b, v82
	v_exp_f32_e32 v82, v82
	v_fmac_f32_e32 v83, 0x7149f2ca, v87
	v_mul_f32_e32 v83, 0x3fb8aa3b, v83
	v_exp_f32_e32 v83, v83
	s_nop 0
	v_pk_mul_f32 v[70:71], v[70:71], v[82:83]
	s_nop 0
	v_add_f32_e32 v82, v86, v70
	v_add_f32_e32 v86, v82, v71
	v_or_b32_e32 v82, 0x6a, v146
	v_sub_u32_e32 v82, v141, v82
	v_mul_i32_i24_e32 v82, s8, v82
	v_ashrrev_i32_e32 v82, 31, v82
	v_cvt_f32_i32_e32 v82, v82
	v_add_f32_e32 v83, v145, v84
	v_add_f32_e32 v84, v145, v85
	v_fmac_f32_e32 v83, 0x7149f2ca, v82
	v_mul_f32_e32 v82, 0x3fb8aa3b, v83
	v_or_b32_e32 v83, 0x6b, v146
	v_sub_u32_e32 v83, v141, v83
	v_mul_i32_i24_e32 v83, s8, v83
	v_ashrrev_i32_e32 v83, 31, v83
	v_cvt_f32_i32_e32 v83, v83
	v_exp_f32_e32 v82, v82
	v_fmac_f32_e32 v84, 0x7149f2ca, v83
	v_mul_f32_e32 v83, 0x3fb8aa3b, v84
	v_exp_f32_e32 v83, v83
	s_nop 0
	v_pk_mul_f32 v[72:73], v[72:73], v[82:83]
	s_nop 0
	v_add_f32_e32 v82, v86, v72
	v_add_f32_e32 v86, v82, v73
	v_or_b32_e32 v82, 0x70, v146
	v_sub_u32_e32 v82, v141, v82
	v_mul_i32_i24_e32 v82, s8, v82
	v_ashrrev_i32_e32 v82, 31, v82
	v_cvt_f32_i32_e32 v87, v82
	ds_read_b128 v[82:85], v114 offset:960
	s_waitcnt lgkmcnt(0)
	v_add_f32_e32 v82, v145, v82
	v_fmac_f32_e32 v82, 0x7149f2ca, v87
	v_or_b32_e32 v87, 0x71, v146
	v_sub_u32_e32 v87, v141, v87
	v_mul_i32_i24_e32 v87, s8, v87
	v_ashrrev_i32_e32 v87, 31, v87
	v_cvt_f32_i32_e32 v87, v87
	v_add_f32_e32 v83, v145, v83
	v_mul_f32_e32 v82, 0x3fb8aa3b, v82
	v_exp_f32_e32 v82, v82
	v_fmac_f32_e32 v83, 0x7149f2ca, v87
	v_mul_f32_e32 v83, 0x3fb8aa3b, v83
	v_exp_f32_e32 v83, v83
	s_nop 0
	v_pk_mul_f32 v[74:75], v[74:75], v[82:83]
	s_nop 0
	v_add_f32_e32 v82, v86, v74
	v_add_f32_e32 v86, v82, v75
	v_or_b32_e32 v82, 0x72, v146
	v_sub_u32_e32 v82, v141, v82
	v_mul_i32_i24_e32 v82, s8, v82
	v_ashrrev_i32_e32 v82, 31, v82
	v_cvt_f32_i32_e32 v82, v82
	v_add_f32_e32 v83, v145, v84
	v_add_f32_e32 v84, v145, v85
	v_fmac_f32_e32 v83, 0x7149f2ca, v82
	v_mul_f32_e32 v82, 0x3fb8aa3b, v83
	v_or_b32_e32 v83, 0x73, v146
	v_sub_u32_e32 v83, v141, v83
	v_mul_i32_i24_e32 v83, s8, v83
	v_ashrrev_i32_e32 v83, 31, v83
	v_cvt_f32_i32_e32 v83, v83
	v_exp_f32_e32 v82, v82
	v_fmac_f32_e32 v84, 0x7149f2ca, v83
	v_mul_f32_e32 v83, 0x3fb8aa3b, v84
	v_exp_f32_e32 v83, v83
	s_nop 0
	v_pk_mul_f32 v[76:77], v[76:77], v[82:83]
	s_nop 0
	v_add_f32_e32 v82, v86, v76
	v_add_f32_e32 v86, v82, v77
	v_or_b32_e32 v82, 0x78, v146
	v_sub_u32_e32 v82, v141, v82
	v_mul_i32_i24_e32 v82, s8, v82
	v_ashrrev_i32_e32 v82, 31, v82
	v_cvt_f32_i32_e32 v87, v82
	ds_read_b128 v[82:85], v114 offset:992
	s_waitcnt lgkmcnt(0)
	v_add_f32_e32 v82, v145, v82
	v_fmac_f32_e32 v82, 0x7149f2ca, v87
	v_or_b32_e32 v87, 0x79, v146
	v_sub_u32_e32 v87, v141, v87
	v_mul_i32_i24_e32 v87, s8, v87
	v_ashrrev_i32_e32 v87, 31, v87
	v_cvt_f32_i32_e32 v87, v87
	v_add_f32_e32 v83, v145, v83
	v_mul_f32_e32 v82, 0x3fb8aa3b, v82
	v_exp_f32_e32 v82, v82
	v_fmac_f32_e32 v83, 0x7149f2ca, v87
	v_mul_f32_e32 v83, 0x3fb8aa3b, v83
	v_exp_f32_e32 v83, v83
	s_nop 0
	v_pk_mul_f32 v[78:79], v[78:79], v[82:83]
	s_nop 0
	v_add_f32_e32 v82, v86, v78
	v_add_f32_e32 v86, v82, v79
	v_or_b32_e32 v82, 0x7a, v146
	v_sub_u32_e32 v82, v141, v82
	v_mul_i32_i24_e32 v82, s8, v82
	v_ashrrev_i32_e32 v82, 31, v82
	v_cvt_f32_i32_e32 v82, v82
	v_add_f32_e32 v83, v145, v84
	v_add_f32_e32 v84, v145, v85
	v_fmac_f32_e32 v83, 0x7149f2ca, v82
	v_mul_f32_e32 v82, 0x3fb8aa3b, v83
	v_or_b32_e32 v83, 0x7b, v146
	v_sub_u32_e32 v83, v141, v83
	v_mul_i32_i24_e32 v83, s8, v83
	v_ashrrev_i32_e32 v83, 31, v83
	v_cvt_f32_i32_e32 v83, v83
	v_exp_f32_e32 v82, v82
	v_fmac_f32_e32 v84, 0x7149f2ca, v83
	v_mul_f32_e32 v83, 0x3fb8aa3b, v84
	v_exp_f32_e32 v83, v83
	s_nop 0
	v_pk_mul_f32 v[80:81], v[80:81], v[82:83]
	s_nop 0
	v_add_f32_e32 v82, v86, v80
	v_add_f32_e32 v157, v82, v81
	v_cvt_pk_bf16_f32 v115, v80, v81
